# dilated attention: skip the per-element mask code on chunks that are fully inside the window (bitwise-identical fast path)
# baseline (speedup 1.0000x reference)
; #define MFMA32(a, b, c) __builtin_amdgcn_mfma_f32_32x32x16_bf16((a), (b), (c), 0, 0, 0)
; template <int NA, int MG>
; __device__ __forceinline__ void attn_pair_unit(const Params& p, int l, int u, LAS unsigned char* pl, int sub, int lane, int& g, const bool own0, const int nu) {
;     ...
;         if (c + 1 < NS) { if (ATT_CVALID(c + 1)) ATT_DMA(c + 1, (g + 1) & 1); }
;         else if (nu >= 0) attn_prefetch0<NA>(p, nu, sub, lane, dl + ((g + 1) & 1) * VTILE);
;         bool use;
;         int cl = 0;
;         if (!NA) { cl = c - sub; use = ATT_CVALID(c) && cl >= 0 && cl <= 4; }
;         else { const int krow = R0 + c; use = (krow >= ua) && (krow <= ub); }
;         if (!use) continue;
;         const unsigned slot = (unsigned)(g & 1) * VTILE;
;         bf16x8 kf[8];
;         asm volatile("ds_read_b128 %0, %8 offset:0\n\tds_read_b128 %1, %8 offset:32\n\tds_read_b128 %2, %8 offset:64\n\tds_read_b128 %3, %8 offset:96\n\t"
;                      "ds_read_b128 %4, %8 offset:128\n\tds_read_b128 %5, %8 offset:160\n\tds_read_b128 %6, %8 offset:192\n\tds_read_b128 %7, %8 offset:224\n\t"
;                      "s_waitcnt lgkmcnt(0)"
;                      : "=&v"(kf[0]), "=&v"(kf[1]), "=&v"(kf[2]), "=&v"(kf[3]), "=&v"(kf[4]), "=&v"(kf[5]), "=&v"(kf[6]), "=&v"(kf[7])
;                      : "v"(plw + slot + koff) : "memory");
;         f32x16 s;
; #pragma unroll
;         for (int i = 0; i < 16; ++i) s[i] = 0.f;
; #pragma unroll
;         for (int kk = 0; kk < 8; ++kk) s = MFMA32(kf[kk], qf[kk], s);
;         float cm = -1e30f;
; #pragma unroll
;         for (int i = 0; i < 16; ++i) {
;             const int kr = (i & 3) + 8 * (i >> 2) + 4 * h;
;             bool valid; float sv = s[i];
;             if (!NA) { const int dj = 32 * cl + kr - r; valid = (dj >= 0) && (dj <= 128); if (cl >= 1 && cl <= 3) valid = true; }
;             else { const int krow = R0 + c, kcol = kstart + kr;
;                 valid = (krow >= rsq) && (krow < rsq + 8) && (kcol >= csq) && (kcol < csq + 16);
;                 const int ro = clampi(krow - iq + 7, 0, 14), co = clampi(kcol - cq + 15, 0, 30); sv += bl[ro * 31 + co]; }
;             sv = valid ? sv : -1e30f; s[i] = sv; cm = fmaxf(cm, sv);
;         }
;         cm = fmaxf(cm, __shfl_xor(cm, 32));
.LBB0_156:
	s_sub_i32 s50, s64, 64
	s_cmp_lt_i32 s50, 0
	s_cbranch_scc1 .LBB0_161
	s_cmp_lt_i32 s50, s82
	s_cselect_b64 s[64:65], -1, 0
	s_cmp_lt_u32 s86, 5
	s_cselect_b64 s[96:97], -1, 0
	s_and_b64 s[64:65], s[64:65], s[96:97]
	s_andn2_b64 vcc, exec, s[64:65]
	s_cbranch_vccnz .LBB0_161
	s_bitcmp1_b32 s93, 0
	s_cselect_b32 s50, 0x2100, 0
	s_add_i32 s50, s50, s67
	v_add_u32_e32 v70, s50, v166
	ds_read_b128 v[66:69], v70 offset:0
	ds_read_b128 v[140:143], v70 offset:32
	ds_read_b128 v[184:187], v70 offset:64
	ds_read_b128 v[188:191], v70 offset:96
	ds_read_b128 v[192:195], v70 offset:128
	ds_read_b128 v[196:199], v70 offset:160
	ds_read_b128 v[210:213], v70 offset:192
	ds_read_b128 v[214:217], v70 offset:224
	s_waitcnt lgkmcnt(0)
	s_add_i32 s64, s86, -1
	v_mfma_f32_32x32x16_bf16 v[66:81], v[66:69], v[110:113], 0
	v_add_u32_e32 v139, s85, v135
	s_cmp_lt_u32 s64, 3
	s_cselect_b64 s[64:65], -1, 0
	v_cmp_gt_u32_e32 vcc, s33, v139
	s_or_b64 vcc, s[64:65], vcc
	v_add_u32_e32 v133, 1, v139
	v_mfma_f32_32x32x16_bf16 v[66:81], v[140:143], v[106:109], v[66:81]
	v_add_u32_e32 v140, 2, v139
	v_mfma_f32_32x32x16_bf16 v[66:81], v[184:187], v[102:105], v[66:81]
	v_mfma_f32_32x32x16_bf16 v[66:81], v[188:191], v[98:101], v[66:81]
	v_mfma_f32_32x32x16_bf16 v[66:81], v[192:195], v[94:97], v[66:81]
	v_mfma_f32_32x32x16_bf16 v[66:81], v[196:199], v[90:93], v[66:81]
	v_mfma_f32_32x32x16_bf16 v[66:81], v[210:213], v[86:89], v[66:81]
	v_mfma_f32_32x32x16_bf16 v[66:81], v[214:217], v[82:85], v[66:81]
	s_nop 11
	s_cmp_lg_u64 s[64:65], 0
	s_cbranch_scc0 .Lmask_slow1
	v_max3_f32 v133, v66, s46, v67
	v_max3_f32 v133, v133, v68, v69
	v_max3_f32 v140, v133, v70, v71
	v_mov_b32_e32 v133, v73
	v_max3_f32 v140, v140, v72, v133
	v_mov_b32_e32 v73, v74
	v_mov_b32_e32 v74, v75
	v_max3_f32 v140, v140, v73, v74
	v_mov_b32_e32 v75, v76
	v_mov_b32_e32 v76, v77
	v_max3_f32 v140, v140, v75, v76
	v_mov_b32_e32 v77, v78
	v_mov_b32_e32 v78, v79
	v_max3_f32 v140, v140, v77, v78
	v_mov_b32_e32 v79, v80
	v_mov_b32_e32 v80, v81
	v_max3_f32 v81, v140, v79, v80
	v_xor_b32_e32 v139, 32, v204
	v_and_b32_e32 v140, 64, v204
	v_add_u32_e32 v140, 64, v140
	v_cmp_lt_i32_e32 vcc, v139, v140
	s_nop 1
	v_cndmask_b32_e32 v139, v204, v139, vcc
	v_lshlrev_b32_e32 v139, 2, v139
	s_branch .Lmask_join1
.Lmask_slow1:
	v_cndmask_b32_e32 v66, v206, v66, vcc
	v_cmp_gt_u32_e32 vcc, s33, v133
	s_or_b64 vcc, s[64:65], vcc
	s_nop 0
	v_cndmask_b32_e32 v67, v206, v67, vcc
	v_cmp_gt_u32_e32 vcc, s33, v140
	s_or_b64 vcc, s[64:65], vcc
	v_add_u32_e32 v140, 3, v139
	v_cndmask_b32_e32 v68, v206, v68, vcc
	v_cmp_gt_u32_e32 vcc, s33, v140
	s_or_b64 vcc, s[64:65], vcc
	v_add_u32_e32 v140, 8, v139
	v_cndmask_b32_e32 v69, v206, v69, vcc
	v_cmp_gt_u32_e32 vcc, s33, v140
	s_or_b64 vcc, s[64:65], vcc
	v_add_u32_e32 v140, 9, v139
	v_cndmask_b32_e32 v70, v206, v70, vcc
	v_cmp_gt_u32_e32 vcc, s33, v140
	v_max3_f32 v133, v66, s46, v67
	s_or_b64 vcc, s[64:65], vcc
	v_max3_f32 v133, v133, v68, v69
	v_cndmask_b32_e32 v71, v206, v71, vcc
	v_max3_f32 v140, v133, v70, v71
	v_add_u32_e32 v133, 10, v139
	v_cmp_gt_u32_e32 vcc, s33, v133
	s_or_b64 vcc, s[64:65], vcc
	v_add_u32_e32 v133, 11, v139
	v_cndmask_b32_e32 v72, v206, v72, vcc
	v_cmp_gt_u32_e32 vcc, s33, v133
	s_or_b64 vcc, s[64:65], vcc
	s_nop 0
	v_cndmask_b32_e32 v133, v206, v73, vcc
	v_add_u32_e32 v73, 16, v139
	v_cmp_gt_u32_e32 vcc, s33, v73
	s_or_b64 vcc, s[64:65], vcc
	v_max3_f32 v140, v140, v72, v133
	v_cndmask_b32_e32 v73, v206, v74, vcc
	v_add_u32_e32 v74, 17, v139
	v_cmp_gt_u32_e32 vcc, s33, v74
	s_or_b64 vcc, s[64:65], vcc
	s_nop 0
	v_cndmask_b32_e32 v74, v206, v75, vcc
	v_add_u32_e32 v75, 18, v139
	v_cmp_gt_u32_e32 vcc, s33, v75
	s_or_b64 vcc, s[64:65], vcc
	v_max3_f32 v140, v140, v73, v74
	v_cndmask_b32_e32 v75, v206, v76, vcc
	v_add_u32_e32 v76, 19, v139
	v_cmp_gt_u32_e32 vcc, s33, v76
	s_or_b64 vcc, s[64:65], vcc
	s_nop 0
	v_cndmask_b32_e32 v76, v206, v77, vcc
	v_add_u32_e32 v77, 24, v139
	v_cmp_gt_u32_e32 vcc, s33, v77
	s_or_b64 vcc, s[64:65], vcc
	v_max3_f32 v140, v140, v75, v76
	v_cndmask_b32_e32 v77, v206, v78, vcc
	v_add_u32_e32 v78, 25, v139
	v_cmp_gt_u32_e32 vcc, s33, v78
	s_or_b64 vcc, s[64:65], vcc
	s_nop 0
	v_cndmask_b32_e32 v78, v206, v79, vcc
	v_add_u32_e32 v79, 26, v139
	v_cmp_gt_u32_e32 vcc, s33, v79
	s_or_b64 vcc, s[64:65], vcc
	v_max3_f32 v140, v140, v77, v78
	v_cndmask_b32_e32 v79, v206, v80, vcc
	v_add_u32_e32 v80, 27, v139
	v_cmp_gt_u32_e32 vcc, s33, v80
	s_or_b64 vcc, s[64:65], vcc
	v_xor_b32_e32 v139, 32, v204
	v_cndmask_b32_e32 v80, v206, v81, vcc
	v_max3_f32 v81, v140, v79, v80
	v_and_b32_e32 v140, 64, v204
	v_add_u32_e32 v140, 64, v140
	v_cmp_lt_i32_e32 vcc, v139, v140
	s_nop 1
	v_cndmask_b32_e32 v139, v204, v139, vcc
	v_lshlrev_b32_e32 v139, 2, v139
; template <int NA, int MG>
; __device__ __forceinline__ void attn_pair_unit(const Params& p, int l, int u, LAS unsigned char* pl, int sub, int lane, int& g, const bool own0, const int nu) {
;     ...
;         cm = fmaxf(cm, __shfl_xor(cm, 32));
;         if (__builtin_amdgcn_ballot_w64(cm > m_run + 8.0f) != 0ull) {
;             const float m_new = fmaxf(m_run, cm), alpha = __builtin_amdgcn_exp2f(m_run - m_new);
;             l_run *= alpha; m_run = m_new;
; #pragma unroll
;             for (int db = 0; db < 4; ++db)
; #pragma unroll
;                 for (int i = 0; i < 16; ++i) o[db][i] *= alpha;
;         }
.Lmask_join1:
	ds_bpermute_b32 v139, v139, v81
	s_waitcnt lgkmcnt(0)
	v_max_f32_e32 v139, v139, v139
	v_max_f32_e32 v81, v81, v139
	v_add_f32_e32 v139, 0x41000000, v122
	v_cmp_gt_f32_e32 vcc, v81, v139
	s_cbranch_vccz .LBB0_160
	v_max_f32_e32 v81, v81, v81
	v_max_f32_e32 v139, v122, v122
	v_max_f32_e32 v81, v139, v81
	v_sub_f32_e32 v122, v122, v81
	v_exp_f32_e32 v122, v122
	s_nop 0
	v_pk_mul_f32 v[64:65], v[64:65], v[122:123] op_sel_hi:[1,0]
	v_pk_mul_f32 v[62:63], v[62:63], v[122:123] op_sel_hi:[1,0]
	v_pk_mul_f32 v[60:61], v[60:61], v[122:123] op_sel_hi:[1,0]
	v_pk_mul_f32 v[58:59], v[58:59], v[122:123] op_sel_hi:[1,0]
	v_pk_mul_f32 v[56:57], v[56:57], v[122:123] op_sel_hi:[1,0]
	v_pk_mul_f32 v[54:55], v[54:55], v[122:123] op_sel_hi:[1,0]
	v_pk_mul_f32 v[52:53], v[52:53], v[122:123] op_sel_hi:[1,0]
	v_pk_mul_f32 v[50:51], v[50:51], v[122:123] op_sel_hi:[1,0]
	v_pk_mul_f32 v[48:49], v[48:49], v[122:123] op_sel_hi:[1,0]
	v_pk_mul_f32 v[46:47], v[46:47], v[122:123] op_sel_hi:[1,0]
	v_pk_mul_f32 v[44:45], v[44:45], v[122:123] op_sel_hi:[1,0]
	v_pk_mul_f32 v[42:43], v[42:43], v[122:123] op_sel_hi:[1,0]
	v_pk_mul_f32 v[40:41], v[40:41], v[122:123] op_sel_hi:[1,0]
	v_pk_mul_f32 v[38:39], v[38:39], v[122:123] op_sel_hi:[1,0]
	v_pk_mul_f32 v[36:37], v[36:37], v[122:123] op_sel_hi:[1,0]
	v_pk_mul_f32 v[34:35], v[34:35], v[122:123] op_sel_hi:[1,0]
	v_pk_mul_f32 v[32:33], v[32:33], v[122:123] op_sel_hi:[1,0]
	v_pk_mul_f32 v[30:31], v[30:31], v[122:123] op_sel_hi:[1,0]
	v_pk_mul_f32 v[28:29], v[28:29], v[122:123] op_sel_hi:[1,0]
	v_pk_mul_f32 v[26:27], v[26:27], v[122:123] op_sel_hi:[1,0]
	v_pk_mul_f32 v[24:25], v[24:25], v[122:123] op_sel_hi:[1,0]
	v_pk_mul_f32 v[22:23], v[22:23], v[122:123] op_sel_hi:[1,0]
	v_pk_mul_f32 v[20:21], v[20:21], v[122:123] op_sel_hi:[1,0]
	v_pk_mul_f32 v[18:19], v[18:19], v[122:123] op_sel_hi:[1,0]
	v_pk_mul_f32 v[16:17], v[16:17], v[122:123] op_sel_hi:[1,0]
	v_pk_mul_f32 v[14:15], v[14:15], v[122:123] op_sel_hi:[1,0]
	v_pk_mul_f32 v[12:13], v[12:13], v[122:123] op_sel_hi:[1,0]
	v_pk_mul_f32 v[10:11], v[10:11], v[122:123] op_sel_hi:[1,0]
	v_pk_mul_f32 v[8:9], v[8:9], v[122:123] op_sel_hi:[1,0]
	v_pk_mul_f32 v[6:7], v[6:7], v[122:123] op_sel_hi:[1,0]
	v_pk_mul_f32 v[4:5], v[4:5], v[122:123] op_sel_hi:[1,0]
	v_pk_mul_f32 v[2:3], v[2:3], v[122:123] op_sel_hi:[1,0]
	v_mul_f32_e32 v123, v123, v122
	v_mov_b32_e32 v122, v81

; #define MFMA32(a, b, c) __builtin_amdgcn_mfma_f32_32x32x16_bf16((a), (b), (c), 0, 0, 0)
; template <int NA, int MG>
; __device__ __forceinline__ void attn_pair_unit(const Params& p, int l, int u, LAS unsigned char* pl, int sub, int lane, int& g, const bool own0, const int nu) {
;     ...
;         if (c + 1 < NS) { if (ATT_CVALID(c + 1)) ATT_DMA(c + 1, (g + 1) & 1); }
;         else if (nu >= 0) attn_prefetch0<NA>(p, nu, sub, lane, dl + ((g + 1) & 1) * VTILE);
;         bool use;
;         int cl = 0;
;         if (!NA) { cl = c - sub; use = ATT_CVALID(c) && cl >= 0 && cl <= 4; }
;         else { const int krow = R0 + c; use = (krow >= ua) && (krow <= ub); }
;         if (!use) continue;
;         const unsigned slot = (unsigned)(g & 1) * VTILE;
;         bf16x8 kf[8];
;         asm volatile("ds_read_b128 %0, %8 offset:0\n\tds_read_b128 %1, %8 offset:32\n\tds_read_b128 %2, %8 offset:64\n\tds_read_b128 %3, %8 offset:96\n\t"
;                      "ds_read_b128 %4, %8 offset:128\n\tds_read_b128 %5, %8 offset:160\n\tds_read_b128 %6, %8 offset:192\n\tds_read_b128 %7, %8 offset:224\n\t"
;                      "s_waitcnt lgkmcnt(0)"
;                      : "=&v"(kf[0]), "=&v"(kf[1]), "=&v"(kf[2]), "=&v"(kf[3]), "=&v"(kf[4]), "=&v"(kf[5]), "=&v"(kf[6]), "=&v"(kf[7])
;                      : "v"(plw + slot + koff) : "memory");
;         f32x16 s;
; #pragma unroll
;         for (int i = 0; i < 16; ++i) s[i] = 0.f;
; #pragma unroll
;         for (int kk = 0; kk < 8; ++kk) s = MFMA32(kf[kk], qf[kk], s);
;         float cm = -1e30f;
; #pragma unroll
;         for (int i = 0; i < 16; ++i) {
;             const int kr = (i & 3) + 8 * (i >> 2) + 4 * h;
;             bool valid; float sv = s[i];
;             if (!NA) { const int dj = 32 * cl + kr - r; valid = (dj >= 0) && (dj <= 128); if (cl >= 1 && cl <= 3) valid = true; }
;             else { const int krow = R0 + c, kcol = kstart + kr;
;                 valid = (krow >= rsq) && (krow < rsq + 8) && (kcol >= csq) && (kcol < csq + 16);
;                 const int ro = clampi(krow - iq + 7, 0, 14), co = clampi(kcol - cq + 15, 0, 30); sv += bl[ro * 31 + co]; }
;             sv = valid ? sv : -1e30f; s[i] = sv; cm = fmaxf(cm, sv);
;         }
;         cm = fmaxf(cm, __shfl_xor(cm, 32));
.LBB0_207:
	s_sub_i32 s50, s74, 64
	s_cmp_lt_i32 s50, 0
	s_cbranch_scc1 .LBB0_212
	s_cmp_lt_i32 s50, s45
	s_cselect_b64 s[74:75], -1, 0
	s_cmp_lt_u32 s94, 5
	s_cselect_b64 s[96:97], -1, 0
	s_and_b64 s[74:75], s[74:75], s[96:97]
	s_andn2_b64 vcc, exec, s[74:75]
	s_cbranch_vccnz .LBB0_212
	s_bitcmp1_b32 s84, 0
	s_cselect_b32 s50, 0x2100, 0
	s_add_i32 s50, s50, s0
	v_add_u32_e32 v0, s50, v143
	ds_read_b128 v[2:5], v0 offset:0
	ds_read_b128 v[6:9], v0 offset:32
	ds_read_b128 v[10:13], v0 offset:64
	ds_read_b128 v[180:183], v0 offset:96
	ds_read_b128 v[184:187], v0 offset:128
	ds_read_b128 v[188:191], v0 offset:160
	ds_read_b128 v[192:195], v0 offset:192
	ds_read_b128 v[196:199], v0 offset:224
	s_waitcnt lgkmcnt(0)
	s_add_i32 s74, s94, -1
	v_mfma_f32_32x32x16_bf16 v[80:95], v[2:5], v[124:127], 0
	v_add_u32_e32 v139, s93, v176
	s_cmp_lt_u32 s74, 3
	s_cselect_b64 s[74:75], -1, 0
	v_cmp_gt_u32_e32 vcc, s33, v139
	s_or_b64 vcc, s[74:75], vcc
	v_add_u32_e32 v2, 1, v139
	v_add_u32_e32 v3, 2, v139
	v_mfma_f32_32x32x16_bf16 v[80:95], v[6:9], v[120:123], v[80:95]
	v_add_u32_e32 v4, 3, v139
	v_add_u32_e32 v6, 9, v139
	v_add_u32_e32 v9, 11, v139
	v_add_u32_e32 v14, 25, v139
	v_mfma_f32_32x32x16_bf16 v[80:95], v[10:13], v[116:119], v[80:95]
	v_add_u32_e32 v12, 19, v139
	v_mfma_f32_32x32x16_bf16 v[80:95], v[180:183], v[112:115], v[80:95]
	v_mfma_f32_32x32x16_bf16 v[80:95], v[184:187], v[108:111], v[80:95]
	v_mfma_f32_32x32x16_bf16 v[80:95], v[188:191], v[104:107], v[80:95]
	v_mfma_f32_32x32x16_bf16 v[80:95], v[192:195], v[100:103], v[80:95]
	v_mfma_f32_32x32x16_bf16 v[80:95], v[196:199], v[96:99], v[80:95]
	s_nop 11
	s_cmp_lg_u64 s[74:75], 0
	s_cbranch_scc0 .Lmask_slow0
	v_mov_b32_e32 v0, v80
	v_mov_b32_e32 v2, v81
	v_mov_b32_e32 v3, v82
	v_mov_b32_e32 v4, v83
	v_max3_f32 v5, v0, s46, v2
	v_max3_f32 v7, v5, v3, v4
	v_mov_b32_e32 v5, v84
	v_mov_b32_e32 v6, v85
	v_max3_f32 v8, v7, v5, v6
	v_mov_b32_e32 v7, v86
	v_mov_b32_e32 v10, v87
	v_max3_f32 v11, v8, v7, v10
	v_mov_b32_e32 v8, v88
	v_mov_b32_e32 v9, v89
	v_max3_f32 v13, v11, v8, v9
	v_mov_b32_e32 v11, v90
	v_mov_b32_e32 v12, v91
	v_max3_f32 v15, v13, v11, v12
	v_mov_b32_e32 v13, v92
	v_mov_b32_e32 v14, v93
	v_max3_f32 v81, v15, v13, v14
	v_mov_b32_e32 v15, v94
	v_mov_b32_e32 v80, v95
	v_max3_f32 v81, v81, v15, v80
	v_xor_b32_e32 v82, 32, v204
	v_and_b32_e32 v83, 64, v204
	v_add_u32_e32 v83, 64, v83
	v_cmp_lt_i32_e32 vcc, v82, v83
	s_nop 1
	v_cndmask_b32_e32 v82, v204, v82, vcc
	v_lshlrev_b32_e32 v82, 2, v82
	s_branch .Lmask_join0
; template <int NA, int MG>
; __device__ __forceinline__ void attn_pair_unit(const Params& p, int l, int u, LAS unsigned char* pl, int sub, int lane, int& g, const bool own0, const int nu) {
;     ...
;         for (int i = 0; i < 16; ++i) {
;             const int kr = (i & 3) + 8 * (i >> 2) + 4 * h;
;             bool valid; float sv = s[i];
;             if (!NA) { const int dj = 32 * cl + kr - r; valid = (dj >= 0) && (dj <= 128); if (cl >= 1 && cl <= 3) valid = true; }
;             else { const int krow = R0 + c, kcol = kstart + kr;
;                 valid = (krow >= rsq) && (krow < rsq + 8) && (kcol >= csq) && (kcol < csq + 16);
;                 const int ro = clampi(krow - iq + 7, 0, 14), co = clampi(kcol - cq + 15, 0, 30); sv += bl[ro * 31 + co]; }
;             sv = valid ? sv : -1e30f; s[i] = sv; cm = fmaxf(cm, sv);
;         }
;         cm = fmaxf(cm, __shfl_xor(cm, 32));
;         if (__builtin_amdgcn_ballot_w64(cm > m_run + 8.0f) != 0ull) {
;             const float m_new = fmaxf(m_run, cm), alpha = __builtin_amdgcn_exp2f(m_run - m_new);
;             l_run *= alpha; m_run = m_new;
; #pragma unroll
;             for (int db = 0; db < 4; ++db)
; #pragma unroll
;                 for (int i = 0; i < 16; ++i) o[db][i] *= alpha;
;         }
.Lmask_slow0:
	v_cndmask_b32_e32 v0, v206, v80, vcc
	v_cmp_gt_u32_e32 vcc, s33, v2
	s_or_b64 vcc, s[74:75], vcc
	v_add_u32_e32 v80, 27, v139
	v_cndmask_b32_e32 v2, v206, v81, vcc
	v_cmp_gt_u32_e32 vcc, s33, v3
	s_or_b64 vcc, s[74:75], vcc
	v_max3_f32 v5, v0, s46, v2
	v_cndmask_b32_e32 v3, v206, v82, vcc
	v_cmp_gt_u32_e32 vcc, s33, v4
	s_or_b64 vcc, s[74:75], vcc
	v_xor_b32_e32 v82, 32, v204
	v_cndmask_b32_e32 v4, v206, v83, vcc
	v_max3_f32 v7, v5, v3, v4
	v_add_u32_e32 v5, 8, v139
	v_cmp_gt_u32_e32 vcc, s33, v5
	s_or_b64 vcc, s[74:75], vcc
	v_and_b32_e32 v83, 64, v204
	v_cndmask_b32_e32 v5, v206, v84, vcc
	v_cmp_gt_u32_e32 vcc, s33, v6
	s_or_b64 vcc, s[74:75], vcc
	v_add_u32_e32 v83, 64, v83
	v_cndmask_b32_e32 v6, v206, v85, vcc
	v_max3_f32 v8, v7, v5, v6
	v_add_u32_e32 v7, 10, v139
	v_cmp_gt_u32_e32 vcc, s33, v7
	s_or_b64 vcc, s[74:75], vcc
	s_nop 0
	v_cndmask_b32_e32 v7, v206, v86, vcc
	v_cmp_gt_u32_e32 vcc, s33, v9
	s_or_b64 vcc, s[74:75], vcc
	v_add_u32_e32 v9, 17, v139
	v_cndmask_b32_e32 v10, v206, v87, vcc
	v_max3_f32 v11, v8, v7, v10
	v_add_u32_e32 v8, 16, v139
	v_cmp_gt_u32_e32 vcc, s33, v8
	s_or_b64 vcc, s[74:75], vcc
	s_nop 0
	v_cndmask_b32_e32 v8, v206, v88, vcc
	v_cmp_gt_u32_e32 vcc, s33, v9
	s_or_b64 vcc, s[74:75], vcc
	s_nop 0
	v_cndmask_b32_e32 v9, v206, v89, vcc
	v_max3_f32 v13, v11, v8, v9
	v_add_u32_e32 v11, 18, v139
	v_cmp_gt_u32_e32 vcc, s33, v11
	s_or_b64 vcc, s[74:75], vcc
	s_nop 0
	v_cndmask_b32_e32 v11, v206, v90, vcc
	v_cmp_gt_u32_e32 vcc, s33, v12
	s_or_b64 vcc, s[74:75], vcc
	s_nop 0
	v_cndmask_b32_e32 v12, v206, v91, vcc
	v_max3_f32 v15, v13, v11, v12
	v_add_u32_e32 v13, 24, v139
	v_cmp_gt_u32_e32 vcc, s33, v13
	s_or_b64 vcc, s[74:75], vcc
	s_nop 0
	v_cndmask_b32_e32 v13, v206, v92, vcc
	v_cmp_gt_u32_e32 vcc, s33, v14
	s_or_b64 vcc, s[74:75], vcc
	s_nop 0
	v_cndmask_b32_e32 v14, v206, v93, vcc
	v_max3_f32 v81, v15, v13, v14
	v_add_u32_e32 v15, 26, v139
	v_cmp_gt_u32_e32 vcc, s33, v15
	s_or_b64 vcc, s[74:75], vcc
	s_nop 0
	v_cndmask_b32_e32 v15, v206, v94, vcc
	v_cmp_gt_u32_e32 vcc, s33, v80
	s_or_b64 vcc, s[74:75], vcc
	s_nop 0
	v_cndmask_b32_e32 v80, v206, v95, vcc
	v_cmp_lt_i32_e32 vcc, v82, v83
	v_max3_f32 v81, v81, v15, v80
	s_nop 0
	v_cndmask_b32_e32 v82, v204, v82, vcc
	v_lshlrev_b32_e32 v82, 2, v82
.Lmask_join0:
	ds_bpermute_b32 v82, v82, v81
	s_waitcnt lgkmcnt(0)
	v_max_f32_e32 v82, v82, v82
	v_max_f32_e32 v81, v81, v82
	v_add_f32_e32 v82, 0x41000000, v138
	v_cmp_gt_f32_e32 vcc, v81, v82
	s_cbranch_vccz .LBB0_211
	v_max_f32_e32 v81, v81, v81
	v_max_f32_e32 v82, v138, v138
	v_max_f32_e32 v81, v82, v81
	v_sub_f32_e32 v82, v138, v81
	v_exp_f32_e32 v82, v82
	v_mov_b32_e32 v138, v81
	v_pk_mul_f32 v[78:79], v[78:79], v[82:83] op_sel_hi:[1,0]
	v_pk_mul_f32 v[76:77], v[76:77], v[82:83] op_sel_hi:[1,0]
	v_pk_mul_f32 v[74:75], v[74:75], v[82:83] op_sel_hi:[1,0]
	v_pk_mul_f32 v[72:73], v[72:73], v[82:83] op_sel_hi:[1,0]
	v_pk_mul_f32 v[70:71], v[70:71], v[82:83] op_sel_hi:[1,0]
	v_pk_mul_f32 v[68:69], v[68:69], v[82:83] op_sel_hi:[1,0]
	v_pk_mul_f32 v[66:67], v[66:67], v[82:83] op_sel_hi:[1,0]
	v_pk_mul_f32 v[64:65], v[64:65], v[82:83] op_sel_hi:[1,0]
	v_pk_mul_f32 v[62:63], v[62:63], v[82:83] op_sel_hi:[1,0]
	v_pk_mul_f32 v[60:61], v[60:61], v[82:83] op_sel_hi:[1,0]
	v_pk_mul_f32 v[58:59], v[58:59], v[82:83] op_sel_hi:[1,0]
	v_pk_mul_f32 v[56:57], v[56:57], v[82:83] op_sel_hi:[1,0]
	v_pk_mul_f32 v[54:55], v[54:55], v[82:83] op_sel_hi:[1,0]
	v_pk_mul_f32 v[52:53], v[52:53], v[82:83] op_sel_hi:[1,0]
	v_pk_mul_f32 v[50:51], v[50:51], v[82:83] op_sel_hi:[1,0]
	v_pk_mul_f32 v[48:49], v[48:49], v[82:83] op_sel_hi:[1,0]
	v_pk_mul_f32 v[46:47], v[46:47], v[82:83] op_sel_hi:[1,0]
	v_pk_mul_f32 v[44:45], v[44:45], v[82:83] op_sel_hi:[1,0]
	v_pk_mul_f32 v[42:43], v[42:43], v[82:83] op_sel_hi:[1,0]
	v_pk_mul_f32 v[40:41], v[40:41], v[82:83] op_sel_hi:[1,0]
	v_pk_mul_f32 v[38:39], v[38:39], v[82:83] op_sel_hi:[1,0]
	v_pk_mul_f32 v[36:37], v[36:37], v[82:83] op_sel_hi:[1,0]
	v_pk_mul_f32 v[34:35], v[34:35], v[82:83] op_sel_hi:[1,0]
	v_pk_mul_f32 v[32:33], v[32:33], v[82:83] op_sel_hi:[1,0]
	v_pk_mul_f32 v[30:31], v[30:31], v[82:83] op_sel_hi:[1,0]
	v_pk_mul_f32 v[28:29], v[28:29], v[82:83] op_sel_hi:[1,0]
	v_pk_mul_f32 v[26:27], v[26:27], v[82:83] op_sel_hi:[1,0]
	v_pk_mul_f32 v[24:25], v[24:25], v[82:83] op_sel_hi:[1,0]
	v_pk_mul_f32 v[22:23], v[22:23], v[82:83] op_sel_hi:[1,0]
	v_pk_mul_f32 v[20:21], v[20:21], v[82:83] op_sel_hi:[1,0]
	v_pk_mul_f32 v[18:19], v[18:19], v[82:83] op_sel_hi:[1,0]
	v_pk_mul_f32 v[16:17], v[16:17], v[82:83] op_sel_hi:[1,0]
	v_mul_f32_e32 v135, v135, v82
